# v34 + retention phase: one static s_setprio 1 for waves 4-7 before the chunk loop (reset after the phase)
# baseline (speedup 1.0000x reference)
.LBB0_324:
	s_or_b64 exec, exec, s[0:1]
	s_add_u32 s68, s84, 0x28400000
	s_addc_u32 s69, s85, 0
	v_readlane_b32 s4, v234, 0
	s_waitcnt vmcnt(9) lgkmcnt(0)
	v_mov_b32_e32 v0, v161
	s_mov_b64 s[0:1], 0x28400000
	s_barrier
	s_movk_i32 s6, 0x100
	s_cmpk_lt_i32 s4, 0x100
	v_readlane_b32 s5, v234, 1
	v_readfirstlane_b32 s3, v0
	s_cbranch_scc0 .LBB0_336
	s_waitcnt vmcnt(8)
	v_lshlrev_b32_e32 v6, 3, v0
	v_ashrrev_i32_e32 v7, 31, v6
	s_waitcnt vmcnt(7)
	v_lshlrev_b64 v[8:9], 1, v[6:7]
	v_lshl_add_u64 v[10:11], s[84:85], 0, v[8:9]
	s_mov_b64 s[8:9], 0x30400000
	s_ashr_i32 s15, s3, 4
	v_and_b32_e32 v1, 15, v0
	s_lshr_b32 s4, s3, 2
	v_lshl_add_u64 v[60:61], v[10:11], 0, s[8:9]
	s_movk_i32 s12, 0x90
	s_movk_i32 s14, 0x210
	v_bfi_b32 v10, -16, s15, v0
	s_waitcnt vmcnt(6)
	v_and_or_b32 v12, s4, 48, v1
	s_add_i32 s9, 0, 0x12600
	s_waitcnt vmcnt(5)
	v_mul_lo_u32 v17, v10, s14
	v_mul_lo_u32 v10, v10, s12
	s_add_i32 s20, 0, 0x11400
	v_bfe_u32 v5, v0, 4, 2
	v_add_u32_e32 v2, 1, v12
	v_and_b32_e32 v13, 31, v0
	v_lshrrev_b32_e32 v14, 3, v0
	v_add_u32_e32 v18, s20, v10
	v_mov_b32_e32 v10, s9
	v_cvt_f32_ubyte0_e32 v63, v2
	v_lshlrev_b32_e32 v2, 3, v13
	v_lshlrev_b32_e32 v7, 4, v13
	v_mul_lo_u32 v13, v14, s12
	v_lshlrev_b32_e32 v16, 4, v5
	s_and_b32 s8, s15, -16
	v_mad_u32_u24 v19, v12, s12, v10
	v_lshlrev_b32_e32 v10, 2, v5
	v_lshlrev_b32_e32 v5, 3, v5
	s_movk_i32 s4, 0x1080
	v_mov_b32_e32 v59, 0
	v_add_u32_e32 v14, s9, v13
	s_add_i32 s15, 0, 0x14a00
	s_ashr_i32 s9, s8, 31
	s_waitcnt vmcnt(4)
	v_mov_b32_e32 v20, s20
	v_lshl_or_b32 v58, v12, 12, v5
	v_bfe_u32 v3, v0, 2, 2
	v_cmp_gt_i32_e64 s[4:5], s4, v0
	v_ashrrev_i32_e32 v56, 5, v0
	v_bfe_u32 v92, v0, 3, 5
	v_and_b32_e32 v15, 7, v0
	v_cmp_gt_i32_e64 s[6:7], s6, v0
	v_mad_u32_u24 v20, v1, s12, v20
	s_andn2_b32 s3, s3, 63
	v_mul_u32_u24_e32 v23, 0x210, v1
	v_add_u32_e32 v95, 0xfffffe00, v0
	v_lshl_add_u32 v96, v0, 2, s15
	v_lshl_add_u64 v[0:1], s[8:9], 1, v[58:59]
	s_add_i32 s12, s3, 0
	v_and_b32_e32 v6, 24, v6
	v_lshl_add_u64 v[64:65], v[0:1], 0, s[0:1]
	v_readlane_b32 s0, v234, 0
	v_ashrrev_i32_e32 v57, 31, v56
	v_lshlrev_b32_e32 v4, 3, v15
	v_lshlrev_b32_e32 v93, 4, v15
	v_mad_u32_u24 v15, v12, s14, 0
	v_or_b32_e32 v3, v5, v3
	v_add_u32_e32 v6, s12, v6
	v_add_u32_e32 v94, s20, v13
	v_mul_lo_u32 v13, v56, s14
	s_movk_i32 s14, 0x220
	s_add_i32 s3, s15, s3
	s_add_i32 s12, s12, 0x14a20
	v_readlane_b32 s1, v234, 1
	v_add_u32_e32 v11, 0, v7
	v_add_u32_e32 v17, s15, v17
	v_mul_lo_u32 v21, v56, s14
	v_mul_u32_u24_e32 v3, 0x220, v3
	v_add_u32_e32 v22, s3, v5
	s_waitcnt vmcnt(3)
	v_add_u32_e32 v24, s12, v5
	s_mov_b32 s12, s0
	s_lshl_b32 s3, s0, 5
	s_mov_b64 s[0:1], 0x30402000
	v_lshlrev_b64 v[70:71], 12, v[56:57]
	s_mov_b32 s13, 0
	v_or_b32_e32 v62, 0xfc0, v12
	s_lshl_b32 s22, s82, 5
	v_lshl_add_u64 v[66:67], v[8:9], 0, s[0:1]
	v_or_b32_e32 v68, 0x20400080, v93
	v_mov_b32_e32 v69, v59
	v_or_b32_e32 v70, v70, v7
	s_mov_b32 s36, 0xc2fc0000
	s_mov_b32 s37, 0x800000
	s_movk_i32 s38, 0xe7f
	v_lshlrev_b32_e32 v72, 1, v2
	s_mov_b32 s39, 0x10000
	s_mov_b32 s40, 0x20000
	s_mov_b32 s41, 0x30000
	v_lshlrev_b32_e32 v74, 1, v4
	s_mov_b64 s[14:15], 0x40000
	s_mov_b64 s[20:21], 0x2000
	s_mov_b64 s[24:25], 0x80
	s_lshl_b64 s[26:27], s[8:9], 1
	v_lshlrev_b32_e32 v58, 1, v10
	v_mov_b32_e32 v97, 0x42800000
	v_mov_b32_e32 v98, 0x42000000
	v_not_b32_e32 v99, 63
	v_add_u32_e32 v100, v11, v13
	v_add_u32_e32 v101, v11, v21
	v_add_u32_e32 v102, v14, v93
	v_add_u32_e32 v103, v15, v16
	v_add_u32_e32 v104, v17, v16
	v_add_u32_e32 v105, v18, v16
	v_add_u32_e32 v106, v19, v16
	v_add_u32_e32 v107, v20, v16
	v_add_u32_e32 v108, v6, v3
	v_add_u32_e32 v109, v22, v23
	v_add_u32_e32 v110, v24, v23
	s_mov_b32 s42, s12
	v_readfirstlane_b32 s98, v185
	s_nop 3
	s_cmp_ge_u32 s98, 4
	s_cbranch_scc0 .Lret_prio
	s_setprio 1
.Lret_prio:
	s_branch .LBB0_327

.LBB0_336:
	s_setprio 0
	s_waitcnt vmcnt(0)
	s_waitcnt lgkmcnt(0)
	s_barrier
	s_and_saveexec_b64 s[0:1], s[78:79]
	s_xor_b64 s[0:1], exec, s[0:1]
	s_cbranch_execz .LBB0_389
	s_add_i32 s3, 0, 0x22800
	v_mov_b32_e32 v0, s3
	s_waitcnt vmcnt(0) expcnt(0) lgkmcnt(0)
	ds_read_b32 v2, v0
	s_add_i32 s3, 0, 0x22804
	v_mov_b32_e32 v0, s3
	ds_read_b32 v0, v0
	s_waitcnt lgkmcnt(1)
	v_cmp_ne_u32_e32 vcc, 0, v2
	s_cbranch_vccnz .LBB0_352
	s_add_u32 s4, s84, 0x4200
	s_addc_u32 s5, s85, 0
	s_add_u32 s6, s84, 0x4400
	s_addc_u32 s7, s85, 0
	s_add_u32 s8, s84, 0x4500
	s_addc_u32 s9, s85, 0
	s_add_u32 s10, s84, 0x4600
	s_addc_u32 s11, s85, 0
	s_add_u32 s12, s84, 0x4700
	s_addc_u32 s13, s85, 0
	s_add_u32 s14, s84, 0x4800
	s_addc_u32 s15, s85, 0
	s_add_u32 s20, s84, 0x4900
	s_addc_u32 s21, s85, 0
	s_add_u32 s24, s84, 0x4a00
	s_addc_u32 s25, s85, 0
	s_add_u32 s26, s84, 0x4b00
	s_addc_u32 s27, s85, 0
	s_add_u32 s28, s84, 0x4c00
	s_addc_u32 s29, s85, 0
	s_add_u32 s30, s84, 0x4d00
	s_addc_u32 s31, s85, 0
	s_add_u32 s34, s84, 0x4e00
	s_addc_u32 s35, s85, 0
	s_add_u32 s36, s84, 0x4f00
	s_addc_u32 s37, s85, 0
	s_add_u32 s38, s84, 0x5000
	s_addc_u32 s39, s85, 0
	s_add_u32 s40, s84, 0x5100
	s_addc_u32 s41, s85, 0
	s_add_u32 s42, s84, 0x5200
	v_readlane_b32 s3, v234, 2
	s_addc_u32 s43, s85, 0
	s_mul_i32 s3, s83, s3
	s_add_u32 s44, s84, 0x5300
	s_mul_i32 s3, s3, s82
	s_addc_u32 s45, s85, 0
	s_mov_b32 s22, 1
	v_mov_b32_e32 v16, 0
	s_branch .LBB0_340
